# sample_outproj body rewritten: residual loads first, all K-loop fragment loads hoisted behind counted waits, epilogue without waits
# speedup vs baseline: 1.0196x; 1.0008x over previous
; __device__ __forceinline__ void sample_outproj(const bf16_t* MIXp, const bf16_t* Wt, int K, const float* Xs  , float* Z, int gw, int NGW, int lane) {
;     ...
;     for (int task = gw; task < 16 * 64; task += NGW) {
;         const int rt = task >> 6, ct = task & 63;
;         const bf16_t* ap = MIXp + (size_t)(NP + rt * 16 + fr) * K + g4 * 8;
;         const bf16_t* bp = Wt + (size_t)(ct * 16 + fr) * K + g4 * 8;
;         f32x4 acc = (f32x4){0.f, 0.f, 0.f, 0.f};
; #pragma unroll 8
;         for (int ks = 0; ks < K / 32; ++ks) { const bf16x8 a = *(const bf16x8*)(ap + ks * 32), b = *(const bf16x8*)(bp + ks * 32);
;             acc = __builtin_amdgcn_mfma_f32_16x16x32_bf16(a, b, acc, 0, 0, 0); }
; #pragma unroll
;         for (int r = 0; r < 4; ++r) { const size_t os = (size_t)(rt * 16 + g4 * 4 + r) * DM + ct * 16 + fr; Z[(size_t)NP * DM + os] = Xs[os] * ALPHA + acc[r]; }
;     }
.LBB0_810:
	s_lshl_b32 s2, s0, 4
	s_and_b32 s2, s2, 0x3f0
	v_add_u32_e32 v160, s7, v14
	v_or_b32_e32 v161, s2, v12
	v_readlane_b32 s2, v253, 8
	v_readlane_b32 s3, v253, 9
	v_lshlrev_b32_e32 v161, 2, v161
	v_lshl_or_b32 v162, v160, 12, v161
	v_add_u32_e32 v163, 0x1000, v162
	v_add_u32_e32 v164, 0x2000, v162
	v_add_u32_e32 v165, 0x3000, v162
	global_load_dword v166, v162, s[12:13]
	global_load_dword v167, v163, s[12:13]
	global_load_dword v168, v164, s[12:13]
	global_load_dword v169, v165, s[12:13]
	v_add_u32_e32 v170, 0x4000000, v162
	v_add_u32_e32 v171, 0x4000000, v163
	v_add_u32_e32 v172, 0x4000000, v164
	v_add_u32_e32 v173, 0x4000000, v165
	v_add_co_u32_e32 v24, vcc, 0x18a00000, v10
	s_nop 1
	v_addc_co_u32_e32 v25, vcc, 0, v11, vcc
	global_load_dwordx4 v[32:35], v[24:25], off
	global_load_dwordx4 v[96:99], v[8:9], off offset:-256
	global_load_dwordx4 v[36:39], v[24:25], off offset:64
	global_load_dwordx4 v[100:103], v[8:9], off offset:-192
	global_load_dwordx4 v[40:43], v[24:25], off offset:128
	global_load_dwordx4 v[104:107], v[8:9], off offset:-128
	global_load_dwordx4 v[44:47], v[24:25], off offset:192
	global_load_dwordx4 v[108:111], v[8:9], off offset:-64
	global_load_dwordx4 v[48:51], v[24:25], off offset:256
	global_load_dwordx4 v[112:115], v[8:9], off
	global_load_dwordx4 v[52:55], v[24:25], off offset:320
	global_load_dwordx4 v[116:119], v[8:9], off offset:64
	global_load_dwordx4 v[56:59], v[24:25], off offset:384
	global_load_dwordx4 v[120:123], v[8:9], off offset:128
	global_load_dwordx4 v[60:63], v[24:25], off offset:448
	global_load_dwordx4 v[124:127], v[8:9], off offset:192
	global_load_dwordx4 v[64:67], v[24:25], off offset:512
	global_load_dwordx4 v[128:131], v[8:9], off offset:256
	global_load_dwordx4 v[68:71], v[24:25], off offset:576
	global_load_dwordx4 v[132:135], v[8:9], off offset:320
	global_load_dwordx4 v[72:75], v[24:25], off offset:640
	global_load_dwordx4 v[136:139], v[8:9], off offset:384
	global_load_dwordx4 v[76:79], v[24:25], off offset:704
	global_load_dwordx4 v[140:143], v[8:9], off offset:448
	global_load_dwordx4 v[80:83], v[24:25], off offset:768
	global_load_dwordx4 v[144:147], v[8:9], off offset:512
	global_load_dwordx4 v[84:87], v[24:25], off offset:832
	global_load_dwordx4 v[148:151], v[8:9], off offset:576
	global_load_dwordx4 v[88:91], v[24:25], off offset:896
	global_load_dwordx4 v[152:155], v[8:9], off offset:640
	global_load_dwordx4 v[92:95], v[24:25], off offset:960
	global_load_dwordx4 v[156:159], v[8:9], off offset:704
	s_waitcnt vmcnt(30)
	v_mfma_f32_16x16x32_bf16 v[0:3], v[32:35], v[96:99], v[0:3]
	s_waitcnt vmcnt(28)
	v_mfma_f32_16x16x32_bf16 v[0:3], v[36:39], v[100:103], v[0:3]
	s_waitcnt vmcnt(26)
	v_mfma_f32_16x16x32_bf16 v[0:3], v[40:43], v[104:107], v[0:3]
	s_waitcnt vmcnt(24)
	v_mfma_f32_16x16x32_bf16 v[0:3], v[44:47], v[108:111], v[0:3]
	s_waitcnt vmcnt(22)
	v_mfma_f32_16x16x32_bf16 v[0:3], v[48:51], v[112:115], v[0:3]
	s_waitcnt vmcnt(20)
	v_mfma_f32_16x16x32_bf16 v[0:3], v[52:55], v[116:119], v[0:3]
	s_waitcnt vmcnt(18)
	v_mfma_f32_16x16x32_bf16 v[0:3], v[56:59], v[120:123], v[0:3]
	s_waitcnt vmcnt(16)
	v_mfma_f32_16x16x32_bf16 v[0:3], v[60:63], v[124:127], v[0:3]
	s_waitcnt vmcnt(14)
	v_mfma_f32_16x16x32_bf16 v[0:3], v[64:67], v[128:131], v[0:3]
	s_waitcnt vmcnt(12)
	v_mfma_f32_16x16x32_bf16 v[0:3], v[68:71], v[132:135], v[0:3]
	s_waitcnt vmcnt(10)
	v_mfma_f32_16x16x32_bf16 v[0:3], v[72:75], v[136:139], v[0:3]
	s_waitcnt vmcnt(8)
	v_mfma_f32_16x16x32_bf16 v[0:3], v[76:79], v[140:143], v[0:3]
	s_waitcnt vmcnt(6)
	v_mfma_f32_16x16x32_bf16 v[0:3], v[80:83], v[144:147], v[0:3]
	s_waitcnt vmcnt(4)
	v_mfma_f32_16x16x32_bf16 v[0:3], v[84:87], v[148:151], v[0:3]
	s_waitcnt vmcnt(2)
	v_mfma_f32_16x16x32_bf16 v[0:3], v[88:91], v[152:155], v[0:3]
	s_waitcnt vmcnt(0)
	v_mfma_f32_16x16x32_bf16 v[0:3], v[92:95], v[156:159], v[0:3]
	s_nop 7
	s_nop 1
	v_fmamk_f32 v0, v166, 0x3fd744fd, v0
	v_fmamk_f32 v1, v167, 0x3fd744fd, v1
	v_fmamk_f32 v2, v168, 0x3fd744fd, v2
	v_fmamk_f32 v3, v169, 0x3fd744fd, v3
	global_store_dword v170, v0, s[2:3]
	global_store_dword v171, v1, s[2:3]
	global_store_dword v172, v2, s[2:3]
	global_store_dword v173, v3, s[2:3]
	v_readlane_b32 s2, v255, 13
	s_add_i32 s0, s0, s2
	v_readlane_b32 s2, v254, 54
	s_add_i32 s5, s5, s2
	s_cmpk_gt_i32 s0, 0x3ff
	v_readlane_b32 s3, v255, 14
	s_cbranch_scc0 .LBB0_809

; __device__ __forceinline__ void sample_outproj(const bf16_t* MIXp, const bf16_t* Wt, int K, const float* Xs  , float* Z, int gw, int NGW, int lane) {
;     ...
;     for (int task = gw; task < 16 * 64; task += NGW) {
;         const int rt = task >> 6, ct = task & 63;
;         const bf16_t* ap = MIXp + (size_t)(NP + rt * 16 + fr) * K + g4 * 8;
;         const bf16_t* bp = Wt + (size_t)(ct * 16 + fr) * K + g4 * 8;
;         f32x4 acc = (f32x4){0.f, 0.f, 0.f, 0.f};
; #pragma unroll 8
;         for (int ks = 0; ks < K / 32; ++ks) { const bf16x8 a = *(const bf16x8*)(ap + ks * 32), b = *(const bf16x8*)(bp + ks * 32);
;             acc = __builtin_amdgcn_mfma_f32_16x16x32_bf16(a, b, acc, 0, 0, 0); }
; #pragma unroll
;         for (int r = 0; r < 4; ++r) { const size_t os = (size_t)(rt * 16 + g4 * 4 + r) * DM + ct * 16 + fr; Z[(size_t)NP * DM + os] = Xs[os] * ALPHA + acc[r]; }
;     }
.LBB0_1563:
	s_lshl_b32 s17, s0, 4
	s_and_b32 s17, s17, 0x3f0
	v_add_u32_e32 v160, s7, v14
	v_or_b32_e32 v161, s17, v12
	v_readlane_b32 s24, v253, 8
	v_readlane_b32 s25, v253, 9
	v_lshlrev_b32_e32 v161, 2, v161
	v_lshl_or_b32 v162, v160, 12, v161
	v_add_u32_e32 v163, 0x1000, v162
	v_add_u32_e32 v164, 0x2000, v162
	v_add_u32_e32 v165, 0x3000, v162
	global_load_dword v166, v162, s[2:3]
	global_load_dword v167, v163, s[2:3]
	global_load_dword v168, v164, s[2:3]
	global_load_dword v169, v165, s[2:3]
	v_add_u32_e32 v170, 0x4000000, v162
	v_add_u32_e32 v171, 0x4000000, v163
	v_add_u32_e32 v172, 0x4000000, v164
	v_add_u32_e32 v173, 0x4000000, v165
	v_add_co_u32_e32 v24, vcc, 0x18a00000, v10
	s_nop 1
	v_addc_co_u32_e32 v25, vcc, 0, v11, vcc
	global_load_dwordx4 v[32:35], v[24:25], off
	global_load_dwordx4 v[96:99], v[8:9], off offset:-256
	global_load_dwordx4 v[36:39], v[24:25], off offset:64
	global_load_dwordx4 v[100:103], v[8:9], off offset:-192
	global_load_dwordx4 v[40:43], v[24:25], off offset:128
	global_load_dwordx4 v[104:107], v[8:9], off offset:-128
	global_load_dwordx4 v[44:47], v[24:25], off offset:192
	global_load_dwordx4 v[108:111], v[8:9], off offset:-64
	global_load_dwordx4 v[48:51], v[24:25], off offset:256
	global_load_dwordx4 v[112:115], v[8:9], off
	global_load_dwordx4 v[52:55], v[24:25], off offset:320
	global_load_dwordx4 v[116:119], v[8:9], off offset:64
	global_load_dwordx4 v[56:59], v[24:25], off offset:384
	global_load_dwordx4 v[120:123], v[8:9], off offset:128
	global_load_dwordx4 v[60:63], v[24:25], off offset:448
	global_load_dwordx4 v[124:127], v[8:9], off offset:192
	global_load_dwordx4 v[64:67], v[24:25], off offset:512
	global_load_dwordx4 v[128:131], v[8:9], off offset:256
	global_load_dwordx4 v[68:71], v[24:25], off offset:576
	global_load_dwordx4 v[132:135], v[8:9], off offset:320
	global_load_dwordx4 v[72:75], v[24:25], off offset:640
	global_load_dwordx4 v[136:139], v[8:9], off offset:384
	global_load_dwordx4 v[76:79], v[24:25], off offset:704
	global_load_dwordx4 v[140:143], v[8:9], off offset:448
	global_load_dwordx4 v[80:83], v[24:25], off offset:768
	global_load_dwordx4 v[144:147], v[8:9], off offset:512
	global_load_dwordx4 v[84:87], v[24:25], off offset:832
	global_load_dwordx4 v[148:151], v[8:9], off offset:576
	global_load_dwordx4 v[88:91], v[24:25], off offset:896
	global_load_dwordx4 v[152:155], v[8:9], off offset:640
	global_load_dwordx4 v[92:95], v[24:25], off offset:960
	global_load_dwordx4 v[156:159], v[8:9], off offset:704
	s_waitcnt vmcnt(30)
	v_mfma_f32_16x16x32_bf16 v[0:3], v[32:35], v[96:99], v[0:3]
	s_waitcnt vmcnt(28)
	v_mfma_f32_16x16x32_bf16 v[0:3], v[36:39], v[100:103], v[0:3]
	s_waitcnt vmcnt(26)
	v_mfma_f32_16x16x32_bf16 v[0:3], v[40:43], v[104:107], v[0:3]
	s_waitcnt vmcnt(24)
	v_mfma_f32_16x16x32_bf16 v[0:3], v[44:47], v[108:111], v[0:3]
	s_waitcnt vmcnt(22)
	v_mfma_f32_16x16x32_bf16 v[0:3], v[48:51], v[112:115], v[0:3]
	s_waitcnt vmcnt(20)
	v_mfma_f32_16x16x32_bf16 v[0:3], v[52:55], v[116:119], v[0:3]
	s_waitcnt vmcnt(18)
	v_mfma_f32_16x16x32_bf16 v[0:3], v[56:59], v[120:123], v[0:3]
	s_waitcnt vmcnt(16)
	v_mfma_f32_16x16x32_bf16 v[0:3], v[60:63], v[124:127], v[0:3]
	global_load_dwordx4 v[32:35], v[24:25], off offset:1024
	global_load_dwordx4 v[96:99], v[8:9], off offset:768
	global_load_dwordx4 v[36:39], v[24:25], off offset:1088
	global_load_dwordx4 v[100:103], v[8:9], off offset:832
	global_load_dwordx4 v[40:43], v[24:25], off offset:1152
	global_load_dwordx4 v[104:107], v[8:9], off offset:896
	global_load_dwordx4 v[44:47], v[24:25], off offset:1216
	global_load_dwordx4 v[108:111], v[8:9], off offset:960
	global_load_dwordx4 v[48:51], v[24:25], off offset:1280
	global_load_dwordx4 v[112:115], v[8:9], off offset:1024
	global_load_dwordx4 v[52:55], v[24:25], off offset:1344
	global_load_dwordx4 v[116:119], v[8:9], off offset:1088
	global_load_dwordx4 v[56:59], v[24:25], off offset:1408
	global_load_dwordx4 v[120:123], v[8:9], off offset:1152
	global_load_dwordx4 v[60:63], v[24:25], off offset:1472
	global_load_dwordx4 v[124:127], v[8:9], off offset:1216
	s_waitcnt vmcnt(30)
; __device__ __forceinline__ void sample_outproj(const bf16_t* MIXp, const bf16_t* Wt, int K, const float* Xs  , float* Z, int gw, int NGW, int lane) {
;     ...
;         f32x4 acc = (f32x4){0.f, 0.f, 0.f, 0.f};
; #pragma unroll 8
;         for (int ks = 0; ks < K / 32; ++ks) { const bf16x8 a = *(const bf16x8*)(ap + ks * 32), b = *(const bf16x8*)(bp + ks * 32);
;             acc = __builtin_amdgcn_mfma_f32_16x16x32_bf16(a, b, acc, 0, 0, 0); }
; #pragma unroll
;         for (int r = 0; r < 4; ++r) { const size_t os = (size_t)(rt * 16 + g4 * 4 + r) * DM + ct * 16 + fr; Z[(size_t)NP * DM + os] = Xs[os] * ALPHA + acc[r]; }
	v_mfma_f32_16x16x32_bf16 v[0:3], v[64:67], v[128:131], v[0:3]
	s_waitcnt vmcnt(28)
	v_mfma_f32_16x16x32_bf16 v[0:3], v[68:71], v[132:135], v[0:3]
	s_waitcnt vmcnt(26)
	v_mfma_f32_16x16x32_bf16 v[0:3], v[72:75], v[136:139], v[0:3]
	s_waitcnt vmcnt(24)
	v_mfma_f32_16x16x32_bf16 v[0:3], v[76:79], v[140:143], v[0:3]
	s_waitcnt vmcnt(22)
	v_mfma_f32_16x16x32_bf16 v[0:3], v[80:83], v[144:147], v[0:3]
	s_waitcnt vmcnt(20)
	v_mfma_f32_16x16x32_bf16 v[0:3], v[84:87], v[148:151], v[0:3]
	s_waitcnt vmcnt(18)
	v_mfma_f32_16x16x32_bf16 v[0:3], v[88:91], v[152:155], v[0:3]
	s_waitcnt vmcnt(16)
	v_mfma_f32_16x16x32_bf16 v[0:3], v[92:95], v[156:159], v[0:3]
	global_load_dwordx4 v[64:67], v[24:25], off offset:1536
	global_load_dwordx4 v[128:131], v[8:9], off offset:1280
	global_load_dwordx4 v[68:71], v[24:25], off offset:1600
	global_load_dwordx4 v[132:135], v[8:9], off offset:1344
	global_load_dwordx4 v[72:75], v[24:25], off offset:1664
	global_load_dwordx4 v[136:139], v[8:9], off offset:1408
	global_load_dwordx4 v[76:79], v[24:25], off offset:1728
	global_load_dwordx4 v[140:143], v[8:9], off offset:1472
	global_load_dwordx4 v[80:83], v[24:25], off offset:1792
	global_load_dwordx4 v[144:147], v[8:9], off offset:1536
	global_load_dwordx4 v[84:87], v[24:25], off offset:1856
	global_load_dwordx4 v[148:151], v[8:9], off offset:1600
	global_load_dwordx4 v[88:91], v[24:25], off offset:1920
	global_load_dwordx4 v[152:155], v[8:9], off offset:1664
	global_load_dwordx4 v[92:95], v[24:25], off offset:1984
	global_load_dwordx4 v[156:159], v[8:9], off offset:1728
	s_waitcnt vmcnt(30)
	v_mfma_f32_16x16x32_bf16 v[0:3], v[32:35], v[96:99], v[0:3]
	s_waitcnt vmcnt(28)
	v_mfma_f32_16x16x32_bf16 v[0:3], v[36:39], v[100:103], v[0:3]
	s_waitcnt vmcnt(26)
	v_mfma_f32_16x16x32_bf16 v[0:3], v[40:43], v[104:107], v[0:3]
	s_waitcnt vmcnt(24)
	v_mfma_f32_16x16x32_bf16 v[0:3], v[44:47], v[108:111], v[0:3]
	s_waitcnt vmcnt(22)
	v_mfma_f32_16x16x32_bf16 v[0:3], v[48:51], v[112:115], v[0:3]
	s_waitcnt vmcnt(20)
	v_mfma_f32_16x16x32_bf16 v[0:3], v[52:55], v[116:119], v[0:3]
	s_waitcnt vmcnt(18)
	v_mfma_f32_16x16x32_bf16 v[0:3], v[56:59], v[120:123], v[0:3]
	s_waitcnt vmcnt(16)
	v_mfma_f32_16x16x32_bf16 v[0:3], v[60:63], v[124:127], v[0:3]
	s_waitcnt vmcnt(14)
	v_mfma_f32_16x16x32_bf16 v[0:3], v[64:67], v[128:131], v[0:3]
	s_waitcnt vmcnt(12)
	v_mfma_f32_16x16x32_bf16 v[0:3], v[68:71], v[132:135], v[0:3]
	s_waitcnt vmcnt(10)
	v_mfma_f32_16x16x32_bf16 v[0:3], v[72:75], v[136:139], v[0:3]
	s_waitcnt vmcnt(8)
	v_mfma_f32_16x16x32_bf16 v[0:3], v[76:79], v[140:143], v[0:3]
	s_waitcnt vmcnt(6)
	v_mfma_f32_16x16x32_bf16 v[0:3], v[80:83], v[144:147], v[0:3]
	s_waitcnt vmcnt(4)
	v_mfma_f32_16x16x32_bf16 v[0:3], v[84:87], v[148:151], v[0:3]
	s_waitcnt vmcnt(2)
	v_mfma_f32_16x16x32_bf16 v[0:3], v[88:91], v[152:155], v[0:3]
	s_waitcnt vmcnt(0)
	v_mfma_f32_16x16x32_bf16 v[0:3], v[92:95], v[156:159], v[0:3]
	s_nop 7
	s_nop 1
	v_fmamk_f32 v0, v166, 0x3fd744fd, v0
	v_fmamk_f32 v1, v167, 0x3fd744fd, v1
	v_fmamk_f32 v2, v168, 0x3fd744fd, v2
	v_fmamk_f32 v3, v169, 0x3fd744fd, v3
	global_store_dword v170, v0, s[24:25]
	global_store_dword v171, v1, s[24:25]
	global_store_dword v172, v2, s[24:25]
	global_store_dword v173, v3, s[24:25]
	v_readlane_b32 s24, v255, 13
	s_add_i32 s0, s0, s24
	v_readlane_b32 s24, v254, 54
	s_add_i32 s5, s5, s24
	s_cmpk_gt_i32 s0, 0x3ff
	v_readlane_b32 s25, v255, 14
	s_cbranch_scc0 .LBB0_1562
